# static priority raise for the four staging/converting waves for the duration of the scan phase's staging loop (s_setprio 1 at entry, 0 before the drain), same code placement; otherwise v78
# baseline (speedup 1.0000x reference)
; #define GAS __attribute__((address_space(1)))
; __device__ __forceinline__ void rwkv_scan_phase(Frame& F, const bf16* RKV, const float* WAG, const bf16* AGB, const float* k_k, const float* k_a, const float* r_k, bf16* Y, float* BS, float* ST2) {
;     ...
;         if (wave >= 4) {
;             const int st = tid - 256, ts = st >> 4, c4 = st & 15;
;             const f32x4 kkc = *(const GAS f32x4*)(k_k + h * 64 + 4 * c4), kac = *(const GAS f32x4*)(k_a + h * 64 + 4 * c4), rkc = *(const GAS f32x4*)(r_k + h * 64 + 4 * c4);
;     ...
;             constexpr int NCH = SEQ / SC_T;
;             v2u RAh[2][4], RBh[2][4]; f32x4 RAw[2], RBw[2];
;             ST_LOAD(RA, 0); ST_LOAD(RB, 1);
;             ST_PROC(RA, 0);
.LBB0_1757:
	s_branch .LBB0_1688
	s_nop 0
	s_nop 0
	s_nop 0
	s_nop 0
	s_nop 0
	s_nop 0
	s_nop 0
	s_nop 0
	s_nop 0
	s_nop 0
	s_nop 0
	s_nop 0
	s_nop 0
	s_nop 0
	s_nop 0
	s_nop 0
	s_nop 0
	s_nop 0
	s_nop 0
	s_nop 0
	s_nop 0
	s_nop 0
	s_nop 0
	s_nop 0
	s_nop 0
	s_nop 0
	s_nop 0
	s_nop 0
	s_nop 0
	s_nop 0
.LBB0_1758:
	s_setprio 1
	s_mul_i32 s70, s52, 4
	s_mul_i32 s65, s96, 4
	s_add_u32 s65, s65, s80
	s_sub_u32 s65, s65, 4
	s_sub_u32 s65, s65, s70
	s_mov_b32 s66, 1
	s_mov_b32 s67, 0
	s_mov_b32 s68, 0
	s_mov_b32 s69, 0
	s_mov_b32 s71, 0
	s_mov_b32 s32, 0
	s_ashr_i32 s48, s55, 6
	s_bfe_u32 s6, s55, 0x50001
	s_ashr_i32 s49, s48, 31
	s_lshl_b64 s[44:45], s[48:49], 22
	s_lshl_b32 s0, s6, 6
	s_or_b32 s44, s44, s0
	s_waitcnt vmcnt(5)
	v_mov_b32_e32 v61, s45
	v_or_b32_e32 v60, s44, v90
	v_lshl_add_u64 v[12:13], v[60:61], 0, v[108:109]
	v_lshlrev_b64 v[14:15], 1, v[12:13]
	s_lshl_b32 s0, s6, 8
	v_lshl_add_u64 v[16:17], s[12:13], 0, v[14:15]
	v_lshl_add_u64 v[0:1], v[94:95], 0, s[0:1]
	v_lshl_add_u64 v[4:5], v[96:97], 0, s[0:1]
	v_lshl_add_u64 v[8:9], v[98:99], 0, s[0:1]
	global_load_dwordx2 v[30:31], v[16:17], off
	v_lshl_add_u64 v[16:17], s[24:25], 0, v[14:15]
	v_lshl_add_u64 v[18:19], s[26:27], 0, v[14:15]
	v_lshl_add_u64 v[12:13], v[12:13], 2, s[14:15]
	global_load_dwordx4 v[0:3], v[0:1], off
	v_lshl_add_u64 v[14:15], s[16:17], 0, v[14:15]
	global_load_dwordx4 v[4:7], v[4:5], off
	s_and_b32 s0, s55, 1
	global_load_dwordx4 v[8:11], v[8:9], off
	s_nop 0
	global_load_dwordx2 v[32:33], v[16:17], off
	global_load_dwordx2 v[42:43], v[18:19], off
	s_nop 0
	global_load_dwordx4 v[16:19], v[12:13], off
	global_load_dwordx2 v[34:35], v[14:15], off
	v_lshl_add_u64 v[12:13], v[60:61], 0, v[112:113]
	v_lshlrev_b64 v[14:15], 1, v[12:13]
	v_lshl_add_u64 v[20:21], s[12:13], 0, v[14:15]
	global_load_dwordx2 v[38:39], v[20:21], off
	v_lshl_add_u64 v[20:21], s[24:25], 0, v[14:15]
	v_lshl_add_u64 v[22:23], s[26:27], 0, v[14:15]
	global_load_dwordx2 v[40:41], v[20:21], off
	global_load_dwordx2 v[36:37], v[22:23], off
	v_lshl_add_u64 v[12:13], v[12:13], 2, s[14:15]
	v_lshl_add_u64 v[20:21], s[16:17], 0, v[14:15]
	global_load_dwordx4 v[12:15], v[12:13], off
	s_nop 0
	global_load_dwordx2 v[44:45], v[20:21], off
	v_lshl_add_u64 v[20:21], v[60:61], 0, v[114:115]
	v_lshlrev_b64 v[22:23], 1, v[20:21]
	s_waitcnt vmcnt(15)
	v_lshl_add_u64 v[24:25], s[12:13], 0, v[22:23]
	global_load_dwordx2 v[64:65], v[24:25], off
	v_lshl_add_u64 v[24:25], s[24:25], 0, v[22:23]
	v_lshl_add_u64 v[26:27], s[26:27], 0, v[22:23]
	v_lshl_add_u64 v[20:21], v[20:21], 2, s[14:15]
	global_load_dwordx2 v[66:67], v[24:25], off
	global_load_dwordx2 v[58:59], v[26:27], off
	v_lshl_add_u64 v[22:23], s[16:17], 0, v[22:23]
	global_load_dwordx4 v[24:27], v[20:21], off
	global_load_dwordx2 v[68:69], v[22:23], off
	v_lshl_add_u64 v[20:21], v[60:61], 0, v[116:117]
	v_lshlrev_b64 v[22:23], 1, v[20:21]
	v_lshl_add_u64 v[28:29], s[12:13], 0, v[22:23]
	global_load_dwordx2 v[54:55], v[28:29], off
	v_lshl_add_u64 v[28:29], s[24:25], 0, v[22:23]
	v_lshl_add_u64 v[20:21], v[20:21], 2, s[14:15]
	v_lshl_add_u64 v[46:47], s[26:27], 0, v[22:23]
	global_load_dwordx2 v[56:57], v[28:29], off
	global_load_dwordx2 v[52:53], v[46:47], off
	v_lshl_add_u64 v[28:29], s[16:17], 0, v[22:23]
	global_load_dwordx4 v[20:23], v[20:21], off
	s_nop 0
	global_load_dwordx2 v[62:63], v[28:29], off
	v_or_b32_e32 v28, s0, v146
	s_lshl_b32 s33, s6, 2
	v_cmp_eq_u32_e64 s[6:7], 0, v28
	s_lshl_b64 s[46:47], s[48:49], 11
	s_add_u32 s50, s3, s33
	s_addc_u32 s51, s34, 0
	s_waitcnt vmcnt(22)
	v_lshlrev_b32_e32 v28, 16, v30
	v_and_b32_e32 v29, 0xffff0000, v30
	v_lshlrev_b32_e32 v30, 16, v31
	v_and_b32_e32 v31, 0xffff0000, v31
	s_waitcnt vmcnt(18)
	v_lshlrev_b32_e32 v74, 16, v32
	v_and_b32_e32 v75, 0xffff0000, v32
	s_waitcnt vmcnt(15)
	v_lshlrev_b32_e32 v46, 16, v34
	v_and_b32_e32 v47, 0xffff0000, v34
	v_lshlrev_b32_e32 v48, 16, v35
	v_and_b32_e32 v49, 0xffff0000, v35
	v_lshlrev_b32_e32 v32, 16, v33
	v_and_b32_e32 v33, 0xffff0000, v33
	v_pk_add_f32 v[34:35], v[48:49], -1.0 op_sel_hi:[1,0]
	v_pk_add_f32 v[72:73], v[46:47], -1.0 op_sel_hi:[1,0]
	v_pk_mul_f32 v[50:51], v[2:3], v[32:33]
	v_pk_mul_f32 v[70:71], v[0:1], v[74:75]
	v_pk_fma_f32 v[80:81], v[4:5], v[72:73], 1.0 op_sel_hi:[1,1,0]
	v_pk_fma_f32 v[34:35], v[6:7], v[34:35], 1.0 op_sel_hi:[1,1,0]
	v_pk_mul_f32 v[76:77], v[50:51], v[50:51]
	v_pk_mul_f32 v[78:79], v[70:71], v[70:71]
	v_pk_mul_f32 v[34:35], v[34:35], v[32:33]
	v_pk_mul_f32 v[32:33], v[80:81], v[74:75]
	v_pk_mov_b32 v[72:73], v[78:79], v[76:77] op_sel:[1,0]
	v_mov_b32_e32 v79, v77
	v_pk_mul_f32 v[74:75], v[32:33], v[28:29]
	v_pk_mul_f32 v[76:77], v[34:35], v[30:31]
	v_pk_mul_f32 v[74:75], v[8:9], v[74:75]
	v_pk_mul_f32 v[76:77], v[10:11], v[76:77]
	v_pk_add_f32 v[72:73], v[72:73], v[78:79]
	v_add_f32_e32 v74, v74, v75
	v_add_f32_e32 v75, v76, v77
	v_add_f32_e32 v72, v72, v73
	v_add_f32_e32 v74, v74, v75
	s_nop 0
	v_add_f32_dpp v72, v72, v72 quad_perm:[1,0,3,2] row_mask:0xf bank_mask:0xf bound_ctrl:1
	v_add_f32_dpp v74, v74, v74 quad_perm:[1,0,3,2] row_mask:0xf bank_mask:0xf bound_ctrl:1
	s_nop 0
	v_add_f32_dpp v72, v72, v72 quad_perm:[2,3,0,1] row_mask:0xf bank_mask:0xf bound_ctrl:1
	v_add_f32_dpp v74, v74, v74 quad_perm:[2,3,0,1] row_mask:0xf bank_mask:0xf bound_ctrl:1
	s_nop 0
	v_add_f32_dpp v72, v72, v72 row_half_mirror row_mask:0xf bank_mask:0xf bound_ctrl:1
	v_add_f32_dpp v74, v74, v74 row_half_mirror row_mask:0xf bank_mask:0xf bound_ctrl:1
	s_nop 0
	v_mov_b32_dpp v73, v72 row_mirror row_mask:0xf bank_mask:0xf bound_ctrl:1
	v_mov_b32_dpp v75, v74 row_mirror row_mask:0xf bank_mask:0xf bound_ctrl:1
	s_and_saveexec_b64 s[8:9], s[6:7]
	s_cbranch_execz .LBB0_1760
	v_lshl_add_u64 v[76:77], s[46:47], 0, v[88:89]
	v_lshlrev_b64 v[76:77], 7, v[76:77]
	v_lshl_add_u64 v[76:77], s[50:51], 0, v[76:77]
	v_add_f32_e32 v74, v74, v75
	global_store_dword v[76:77], v74, off

; __device__ __forceinline__ void rwkv_scan_phase(Frame& F, const bf16* RKV, const float* WAG, const bf16* AGB, const float* k_k, const float* k_a, const float* r_k, bf16* Y, float* BS, float* ST2) {
;     ...
;             ST_FLUSH(NCH - 1);
;     ...
;         } else {
.LBB0_1812:
	s_setprio 0
	s_cmp_lt_u32 s80, 4
	s_cbranch_scc1 .Lcsd_dskip
